# k16 with the SwiGLU table's two sum-of-squares loads issued at the top of each tile (before the K loop, free registers) so the epilogue table build needs no memory wait
# speedup vs baseline: 1.0008x; 1.0008x over previous
; template <class Epi>
; __device__ __forceinline__ void gemm_phase(LAS unsigned char* lds, const Gemm g, const StaticOrder& S, const Epi& E, int wave_s) {
;     ...
;         const bool has_next = S.next(ui + 1, nxt);
;         const char* nA = has_next ? (const char*)g.A + (size_t)nxt.pm * tstepA : cA; const char* nB = has_next ? (const char*)g.Bt + (size_t)nxt.pn * tstepB : cB;
;     ...
; #pragma unroll
;         for (int a = 0; a < 2; ++a)
; #pragma unroll
;             for (int b = 0; b < 2; ++b)
; #pragma unroll
;                 for (int m = 0; m < 4; ++m)
; #pragma unroll
;                     for (int n = 0; n < 2; ++n) acc[a][b][m][n] = (f32x4){0.f, 0.f, 0.f, 0.f};
.LBB0_240:
	s_ashr_i32 s25, s24, 31
	s_lshl_b64 s[26:27], s[24:25], 19
	s_add_u32 s26, s0, s26
	s_addc_u32 s27, s1, s27
	s_and_b64 s[30:31], s[6:7], exec
	s_cselect_b32 s9, s27, s35
	s_cselect_b32 s25, s26, s34
	s_ashr_i32 s23, s22, 31
	s_lshl_b64 s[30:31], s[22:23], 19
	s_add_u32 s30, s29, s30
	s_addc_u32 s31, s33, s31
	s_and_b64 s[38:39], s[6:7], exec
	s_cselect_b32 s23, s31, s37
	s_cselect_b32 s57, s30, s36
	s_add_u32 s34, s34, 0x40080
	s_addc_u32 s35, s35, 0
	s_add_u32 s58, s36, 0x100
	v_mov_b32_e32 v0, 0
	s_addc_u32 s59, s37, 0
	s_mov_b32 s60, -2
	v_mov_b32_e32 v1, v0
	v_mov_b32_e32 v2, v0
	v_mov_b32_e32 v3, v0
	v_mov_b32_e32 v4, v0
	v_mov_b32_e32 v5, v0
	v_mov_b32_e32 v6, v0
	v_mov_b32_e32 v7, v0
	v_mov_b32_e32 v8, v0
	v_mov_b32_e32 v9, v0
	v_mov_b32_e32 v10, v0
	v_mov_b32_e32 v11, v0
	v_mov_b32_e32 v12, v0
	v_mov_b32_e32 v13, v0
	v_mov_b32_e32 v14, v0
	v_mov_b32_e32 v15, v0
	s_nop 1
	v_mfma_f32_32x32x16_bf16 v[16:31], v[0:3], v[4:7], 0
	v_mfma_f32_32x32x16_bf16 v[32:47], v[0:3], v[4:7], 0
	v_mfma_f32_32x32x16_bf16 v[48:63], v[0:3], v[4:7], 0
	v_mfma_f32_32x32x16_bf16 v[64:79], v[0:3], v[4:7], 0
	v_mfma_f32_32x32x16_bf16 v[80:95], v[0:3], v[4:7], 0
	v_mfma_f32_32x32x16_bf16 v[96:111], v[0:3], v[4:7], 0
	v_mfma_f32_32x32x16_bf16 v[112:127], v[0:3], v[4:7], 0
	v_readlane_b32 vcc_lo, v254, 7
	v_mbcnt_lo_u32_b32 v226, -1, 0
	v_mbcnt_hi_u32_b32 v226, -1, v226
	v_lshrrev_b32_e32 v227, 1, v226
	v_lshl_add_u32 v227, vcc_lo, 5, v227
	v_and_b32_e32 v228, 1, v226
	v_lshl_add_u32 v229, s8, 8, v227
	v_lshlrev_b32_e32 v229, 6, v229
	v_lshl_add_u32 v229, v228, 5, v229
	global_load_dwordx4 v[230:233], v229, s[14:15]
	global_load_dwordx4 v[234:237], v229, s[14:15] offset:16

; __device__ __forceinline__ unsigned cvtpk(float lo, float hi) { f32x2_t v = {lo, hi}; bf16x2_t b = __builtin_convertvector(v, bf16x2_t); return __builtin_bit_cast(unsigned, b); }
;     __device__ __forceinline__ void operator()(const f32x4 (&acc)[2][2][4][2], const Unit& u, int wr, int wc, int fr, int fq) const {
;         const int row0 = u.pm * BM + wr * 64 + fr, col0 = u.pn * 128 + wc * 32 + 8 * fq;
; #pragma unroll
;         for (int ai = 0; ai < 2; ++ai)
; #pragma unroll
;             for (int m = 0; m < 4; ++m) {
;                 const int row = row0 + ai * HALF + m * 16;
;                 const float rs = 1.0f / sqrtf(ssq_sum(ssq + (size_t)row * 16) * (1.0f / DM) + EPS);
;                 float hv[8];
; #pragma unroll
;                 for (int n = 0; n < 2; ++n)
; #pragma unroll
;                     for (int e = 0; e < 4; ++e) {
;                         const float gg = acc[ai][0][m][n][e] * rs, uu = acc[ai][1][m][n][e] * rs;
;                         const float den = 1.0f + __builtin_amdgcn_exp2f(-gg * LOG2E);
;                         hv[n * 4 + e] = gg * uu * __builtin_amdgcn_rcpf(den);
;                     }
;                 u32x4 w; w.x = cvtpk(hv[0], hv[1]); w.y = cvtpk(hv[2], hv[3]); w.z = cvtpk(hv[4], hv[5]); w.w = cvtpk(hv[6], hv[7]);
;                 *(u32x4*)(H + (size_t)row * DFF + col0) = w;
;             }
.LBB0_244:
	v_readlane_b32 s9, v254, 7
	v_mbcnt_lo_u32_b32 v144, -1, 0
	v_mbcnt_hi_u32_b32 v144, -1, v144
	v_lshrrev_b32_e32 v145, 1, v144
	v_lshl_add_u32 v145, s9, 5, v145
	v_and_b32_e32 v146, 1, v144
	v_lshl_add_u32 v148, s8, 8, v152
	v_mov_b64_e32 v[146:147], s[16:17]
	v_mad_i64_i32 v[176:177], s[8:9], v148, s56, v[146:147]
	v_lshl_or_b32 v150, s2, 7, v154
	v_mov_b32_e32 v151, 0
	v_lshlrev_b64 v[150:151], 1, v[150:151]
	v_lshl_add_u64 v[176:177], v[176:177], 0, v[150:151]
	v_lshlrev_b32_e32 v145, 3, v145
	v_add_u32_e32 v145, 0x20100, v145
	v_lshlrev_b32_e32 v146, 3, v152
	v_add_u32_e32 v146, 0x20100, v146
	s_mov_b32 s9, 0
	v_pk_add_f32 v[160:161], v[230:231], v[232:233]
	v_pk_add_f32 v[164:165], v[234:235], v[236:237]
	v_pk_add_f32 v[160:161], v[160:161], v[164:165]
	v_add_f32_e32 v160, v160, v161
	s_nop 1
	v_add_f32_dpp v160, v160, v160 quad_perm:[1,0,3,2] row_mask:0xf bank_mask:0xf
	v_fmamk_f32 v160, v160, 0x3a800000, v158
	v_rsq_f32_e32 v161, v160
	s_nop 0
	v_mul_f32_e32 v161, 0xbfb8aa3b, v161
	ds_write_b64 v145, v[160:161]
	s_waitcnt lgkmcnt(0)
	s_barrier
	s_waitcnt vmcnt(0)
	ds_read_b64 v[160:161], v146 offset:0
	ds_read_b64 v[162:163], v146 offset:128
	ds_read_b64 v[164:165], v146 offset:256
	ds_read_b64 v[166:167], v146 offset:384
	ds_read_b64 v[168:169], v146 offset:1024
	ds_read_b64 v[170:171], v146 offset:1152
	ds_read_b64 v[172:173], v146 offset:1280
	ds_read_b64 v[174:175], v146 offset:1408
	v_pk_mul_f32 v[116:117], v[124:125], v[116:117]
	v_pk_mul_f32 v[118:119], v[126:127], v[118:119]
	v_pk_mul_f32 v[112:113], v[120:121], v[112:113]
	v_pk_mul_f32 v[114:115], v[122:123], v[114:115]
	s_waitcnt lgkmcnt(7)
	v_mov_b32_e32 v150, v161
	v_pk_mul_f32 v[124:125], v[124:125], v[150:151] op_sel_hi:[1,0]
	v_pk_mul_f32 v[126:127], v[126:127], v[150:151] op_sel_hi:[1,0]
	v_pk_mul_f32 v[120:121], v[120:121], v[150:151] op_sel_hi:[1,0]
	v_pk_mul_f32 v[122:123], v[122:123], v[150:151] op_sel_hi:[1,0]
	v_exp_f32_e32 v124, v124
	v_exp_f32_e32 v125, v125
	v_exp_f32_e32 v126, v126
	v_exp_f32_e32 v127, v127
	v_exp_f32_e32 v120, v120
	v_exp_f32_e32 v121, v121
	v_exp_f32_e32 v122, v122
	v_exp_f32_e32 v123, v123
	v_fma_f32 v124, v124, v160, v160
	v_fma_f32 v125, v125, v160, v160
	v_fma_f32 v126, v126, v160, v160
	v_fma_f32 v127, v127, v160, v160
	v_fma_f32 v120, v120, v160, v160
	v_fma_f32 v121, v121, v160, v160
	v_fma_f32 v122, v122, v160, v160
	v_fma_f32 v123, v123, v160, v160
	v_rcp_f32_e32 v124, v124
	v_rcp_f32_e32 v125, v125
	v_rcp_f32_e32 v126, v126
	v_rcp_f32_e32 v127, v127
	v_rcp_f32_e32 v120, v120
	v_rcp_f32_e32 v121, v121
	v_rcp_f32_e32 v122, v122
	v_rcp_f32_e32 v123, v123
	v_pk_mul_f32 v[116:117], v[116:117], v[124:125]
	v_pk_mul_f32 v[118:119], v[118:119], v[126:127]
	v_pk_mul_f32 v[112:113], v[112:113], v[120:121]
	v_pk_mul_f32 v[114:115], v[114:115], v[122:123]
	v_cvt_pk_bf16_f32 v124, v116, v117
	v_cvt_pk_bf16_f32 v125, v118, v119
	v_cvt_pk_bf16_f32 v126, v112, v113
	v_cvt_pk_bf16_f32 v127, v114, v115
	global_store_dwordx4 v[176:177], v[124:127], off
	v_pk_mul_f32 v[100:101], v[108:109], v[100:101]
	v_pk_mul_f32 v[102:103], v[110:111], v[102:103]
	v_pk_mul_f32 v[96:97], v[104:105], v[96:97]
	v_pk_mul_f32 v[98:99], v[106:107], v[98:99]
	s_waitcnt lgkmcnt(6)
	v_mov_b32_e32 v150, v163
	v_pk_mul_f32 v[108:109], v[108:109], v[150:151] op_sel_hi:[1,0]
	v_pk_mul_f32 v[110:111], v[110:111], v[150:151] op_sel_hi:[1,0]
	v_pk_mul_f32 v[104:105], v[104:105], v[150:151] op_sel_hi:[1,0]
	v_pk_mul_f32 v[106:107], v[106:107], v[150:151] op_sel_hi:[1,0]
	v_exp_f32_e32 v108, v108
	v_exp_f32_e32 v109, v109
	v_exp_f32_e32 v110, v110
	v_exp_f32_e32 v111, v111
	v_exp_f32_e32 v104, v104
	v_exp_f32_e32 v105, v105
	v_exp_f32_e32 v106, v106
	v_exp_f32_e32 v107, v107
	v_fma_f32 v108, v108, v162, v162
	v_fma_f32 v109, v109, v162, v162
	v_fma_f32 v110, v110, v162, v162
	v_fma_f32 v111, v111, v162, v162
	v_fma_f32 v104, v104, v162, v162
	v_fma_f32 v105, v105, v162, v162
	v_fma_f32 v106, v106, v162, v162
	v_fma_f32 v107, v107, v162, v162
	v_rcp_f32_e32 v108, v108
	v_rcp_f32_e32 v109, v109
	v_rcp_f32_e32 v110, v110
	v_rcp_f32_e32 v111, v111
	v_rcp_f32_e32 v104, v104
	v_rcp_f32_e32 v105, v105
	v_rcp_f32_e32 v106, v106
	v_rcp_f32_e32 v107, v107
	s_mov_b32 s8, 0x16000
	v_pk_mul_f32 v[100:101], v[100:101], v[108:109]
	v_pk_mul_f32 v[102:103], v[102:103], v[110:111]
	v_pk_mul_f32 v[96:97], v[96:97], v[104:105]
	v_pk_mul_f32 v[98:99], v[98:99], v[106:107]
	v_cvt_pk_bf16_f32 v108, v100, v101
	v_cvt_pk_bf16_f32 v109, v102, v103
	v_cvt_pk_bf16_f32 v110, v96, v97
	v_cvt_pk_bf16_f32 v111, v98, v99
	v_lshl_add_u64 v[178:179], v[176:177], 0, s[8:9]
	global_store_dwordx4 v[178:179], v[108:111], off
	v_pk_mul_f32 v[84:85], v[92:93], v[84:85]
	v_pk_mul_f32 v[86:87], v[94:95], v[86:87]
	v_pk_mul_f32 v[80:81], v[88:89], v[80:81]
	v_pk_mul_f32 v[82:83], v[90:91], v[82:83]
	s_waitcnt lgkmcnt(5)
	v_mov_b32_e32 v150, v165
	v_pk_mul_f32 v[92:93], v[92:93], v[150:151] op_sel_hi:[1,0]
	v_pk_mul_f32 v[94:95], v[94:95], v[150:151] op_sel_hi:[1,0]
	v_pk_mul_f32 v[88:89], v[88:89], v[150:151] op_sel_hi:[1,0]
	v_pk_mul_f32 v[90:91], v[90:91], v[150:151] op_sel_hi:[1,0]
	v_exp_f32_e32 v92, v92
	v_exp_f32_e32 v93, v93
	v_exp_f32_e32 v94, v94
	v_exp_f32_e32 v95, v95
	v_exp_f32_e32 v88, v88
	v_exp_f32_e32 v89, v89
	v_exp_f32_e32 v90, v90
	v_exp_f32_e32 v91, v91
	v_fma_f32 v92, v92, v164, v164
	v_fma_f32 v93, v93, v164, v164
	v_fma_f32 v94, v94, v164, v164
	v_fma_f32 v95, v95, v164, v164
	v_fma_f32 v88, v88, v164, v164
	v_fma_f32 v89, v89, v164, v164
	v_fma_f32 v90, v90, v164, v164
	v_fma_f32 v91, v91, v164, v164
	v_rcp_f32_e32 v92, v92
	v_rcp_f32_e32 v93, v93
	v_rcp_f32_e32 v94, v94
	v_rcp_f32_e32 v95, v95
	v_rcp_f32_e32 v88, v88
	v_rcp_f32_e32 v89, v89
	v_rcp_f32_e32 v90, v90
	v_rcp_f32_e32 v91, v91
	s_mov_b32 s8, 0x2c000
	v_pk_mul_f32 v[84:85], v[84:85], v[92:93]
	v_pk_mul_f32 v[86:87], v[86:87], v[94:95]
	v_pk_mul_f32 v[80:81], v[80:81], v[88:89]
	v_pk_mul_f32 v[82:83], v[82:83], v[90:91]
	v_cvt_pk_bf16_f32 v92, v84, v85
	v_cvt_pk_bf16_f32 v93, v86, v87
	v_cvt_pk_bf16_f32 v94, v80, v81
	v_cvt_pk_bf16_f32 v95, v82, v83
	v_lshl_add_u64 v[178:179], v[176:177], 0, s[8:9]
	global_store_dwordx4 v[178:179], v[92:95], off
	v_pk_mul_f32 v[68:69], v[76:77], v[68:69]
	v_pk_mul_f32 v[70:71], v[78:79], v[70:71]
	v_pk_mul_f32 v[64:65], v[72:73], v[64:65]
	v_pk_mul_f32 v[66:67], v[74:75], v[66:67]
	s_waitcnt lgkmcnt(4)
; __device__ __forceinline__ unsigned cvtpk(float lo, float hi) { f32x2_t v = {lo, hi}; bf16x2_t b = __builtin_convertvector(v, bf16x2_t); return __builtin_bit_cast(unsigned, b); }
;     __device__ __forceinline__ void operator()(const f32x4 (&acc)[2][2][4][2], const Unit& u, int wr, int wc, int fr, int fq) const {
;     ...
;                     for (int e = 0; e < 4; ++e) {
;                         const float gg = acc[ai][0][m][n][e] * rs, uu = acc[ai][1][m][n][e] * rs;
;                         const float den = 1.0f + __builtin_amdgcn_exp2f(-gg * LOG2E);
;                         hv[n * 4 + e] = gg * uu * __builtin_amdgcn_rcpf(den);
;                     }
;                 u32x4 w; w.x = cvtpk(hv[0], hv[1]); w.y = cvtpk(hv[2], hv[3]); w.z = cvtpk(hv[4], hv[5]); w.w = cvtpk(hv[6], hv[7]);
;                 *(u32x4*)(H + (size_t)row * DFF + col0) = w;
	v_mov_b32_e32 v150, v167
	v_pk_mul_f32 v[76:77], v[76:77], v[150:151] op_sel_hi:[1,0]
	v_pk_mul_f32 v[78:79], v[78:79], v[150:151] op_sel_hi:[1,0]
	v_pk_mul_f32 v[72:73], v[72:73], v[150:151] op_sel_hi:[1,0]
	v_pk_mul_f32 v[74:75], v[74:75], v[150:151] op_sel_hi:[1,0]
	v_exp_f32_e32 v76, v76
	v_exp_f32_e32 v77, v77
	v_exp_f32_e32 v78, v78
	v_exp_f32_e32 v79, v79
	v_exp_f32_e32 v72, v72
	v_exp_f32_e32 v73, v73
	v_exp_f32_e32 v74, v74
	v_exp_f32_e32 v75, v75
	v_fma_f32 v76, v76, v166, v166
	v_fma_f32 v77, v77, v166, v166
	v_fma_f32 v78, v78, v166, v166
	v_fma_f32 v79, v79, v166, v166
	v_fma_f32 v72, v72, v166, v166
	v_fma_f32 v73, v73, v166, v166
	v_fma_f32 v74, v74, v166, v166
	v_fma_f32 v75, v75, v166, v166
	v_rcp_f32_e32 v76, v76
	v_rcp_f32_e32 v77, v77
	v_rcp_f32_e32 v78, v78
	v_rcp_f32_e32 v79, v79
	v_rcp_f32_e32 v72, v72
	v_rcp_f32_e32 v73, v73
	v_rcp_f32_e32 v74, v74
	v_rcp_f32_e32 v75, v75
	s_mov_b32 s8, 0x42000
	v_pk_mul_f32 v[68:69], v[68:69], v[76:77]
	v_pk_mul_f32 v[70:71], v[70:71], v[78:79]
	v_pk_mul_f32 v[64:65], v[64:65], v[72:73]
	v_pk_mul_f32 v[66:67], v[66:67], v[74:75]
	v_cvt_pk_bf16_f32 v76, v68, v69
	v_cvt_pk_bf16_f32 v77, v70, v71
	v_cvt_pk_bf16_f32 v78, v64, v65
	v_cvt_pk_bf16_f32 v79, v66, v67
	v_lshl_add_u64 v[178:179], v[176:177], 0, s[8:9]
	global_store_dwordx4 v[178:179], v[76:79], off
	v_pk_mul_f32 v[52:53], v[60:61], v[52:53]
	v_pk_mul_f32 v[54:55], v[62:63], v[54:55]
	v_pk_mul_f32 v[48:49], v[56:57], v[48:49]
	v_pk_mul_f32 v[50:51], v[58:59], v[50:51]
	s_waitcnt lgkmcnt(3)
	v_mov_b32_e32 v150, v169
	v_pk_mul_f32 v[60:61], v[60:61], v[150:151] op_sel_hi:[1,0]
	v_pk_mul_f32 v[62:63], v[62:63], v[150:151] op_sel_hi:[1,0]
	v_pk_mul_f32 v[56:57], v[56:57], v[150:151] op_sel_hi:[1,0]
	v_pk_mul_f32 v[58:59], v[58:59], v[150:151] op_sel_hi:[1,0]
	v_exp_f32_e32 v60, v60
	v_exp_f32_e32 v61, v61
	v_exp_f32_e32 v62, v62
	v_exp_f32_e32 v63, v63
	v_exp_f32_e32 v56, v56
	v_exp_f32_e32 v57, v57
	v_exp_f32_e32 v58, v58
	v_exp_f32_e32 v59, v59
	v_fma_f32 v60, v60, v168, v168
	v_fma_f32 v61, v61, v168, v168
	v_fma_f32 v62, v62, v168, v168
	v_fma_f32 v63, v63, v168, v168
	v_fma_f32 v56, v56, v168, v168
	v_fma_f32 v57, v57, v168, v168
	v_fma_f32 v58, v58, v168, v168
	v_fma_f32 v59, v59, v168, v168
	v_rcp_f32_e32 v60, v60
	v_rcp_f32_e32 v61, v61
	v_rcp_f32_e32 v62, v62
	v_rcp_f32_e32 v63, v63
	v_rcp_f32_e32 v56, v56
	v_rcp_f32_e32 v57, v57
	v_rcp_f32_e32 v58, v58
	v_rcp_f32_e32 v59, v59
	s_mov_b32 s8, 0xb0000
	v_pk_mul_f32 v[52:53], v[52:53], v[60:61]
	v_pk_mul_f32 v[54:55], v[54:55], v[62:63]
	v_pk_mul_f32 v[48:49], v[48:49], v[56:57]
	v_pk_mul_f32 v[50:51], v[50:51], v[58:59]
	v_cvt_pk_bf16_f32 v60, v52, v53
	v_cvt_pk_bf16_f32 v61, v54, v55
	v_cvt_pk_bf16_f32 v62, v48, v49
	v_cvt_pk_bf16_f32 v63, v50, v51
	v_lshl_add_u64 v[178:179], v[176:177], 0, s[8:9]
	global_store_dwordx4 v[178:179], v[60:63], off
	v_pk_mul_f32 v[36:37], v[44:45], v[36:37]
	v_pk_mul_f32 v[38:39], v[46:47], v[38:39]
	v_pk_mul_f32 v[32:33], v[40:41], v[32:33]
	v_pk_mul_f32 v[34:35], v[42:43], v[34:35]
	s_waitcnt lgkmcnt(2)
; __device__ __forceinline__ unsigned cvtpk(float lo, float hi) { f32x2_t v = {lo, hi}; bf16x2_t b = __builtin_convertvector(v, bf16x2_t); return __builtin_bit_cast(unsigned, b); }
; #define PG8_BAR __builtin_amdgcn_s_barrier()
; template <class Epi>
; __device__ __forceinline__ void gemm_phase(LAS unsigned char* lds, const Gemm g, const StaticOrder& S, const Epi& E, int wave_s) {
;     ...
;         if (!has_next) break;
; #pragma unroll
;         for (int a = 0; a < 2; ++a)
; #pragma unroll
;             for (int b = 0; b < 2; ++b)
; #pragma unroll
;                 for (int m = 0; m < 4; ++m)
; #pragma unroll
;                     for (int n = 0; n < 2; ++n) acc[a][b][m][n] = (f32x4){0.f, 0.f, 0.f, 0.f};
;         cur = nxt; cA = nA; cB = nB; ++ui;
;         if (wr == 1) PG8_BAR;
;     __device__ __forceinline__ void operator()(const f32x4 (&acc)[2][2][4][2], const Unit& u, int wr, int wc, int fr, int fq) const {
;     ...
;                     for (int e = 0; e < 4; ++e) {
;                         const float gg = acc[ai][0][m][n][e] * rs, uu = acc[ai][1][m][n][e] * rs;
;                         const float den = 1.0f + __builtin_amdgcn_exp2f(-gg * LOG2E);
;                         hv[n * 4 + e] = gg * uu * __builtin_amdgcn_rcpf(den);
;                     }
;                 u32x4 w; w.x = cvtpk(hv[0], hv[1]); w.y = cvtpk(hv[2], hv[3]); w.z = cvtpk(hv[4], hv[5]); w.w = cvtpk(hv[6], hv[7]);
;                 *(u32x4*)(H + (size_t)row * DFF + col0) = w;
	v_mov_b32_e32 v150, v171
	v_pk_mul_f32 v[44:45], v[44:45], v[150:151] op_sel_hi:[1,0]
	v_pk_mul_f32 v[46:47], v[46:47], v[150:151] op_sel_hi:[1,0]
	v_pk_mul_f32 v[40:41], v[40:41], v[150:151] op_sel_hi:[1,0]
	v_pk_mul_f32 v[42:43], v[42:43], v[150:151] op_sel_hi:[1,0]
	v_exp_f32_e32 v44, v44
	v_exp_f32_e32 v45, v45
	v_exp_f32_e32 v46, v46
	v_exp_f32_e32 v47, v47
	v_exp_f32_e32 v40, v40
	v_exp_f32_e32 v41, v41
	v_exp_f32_e32 v42, v42
	v_exp_f32_e32 v43, v43
	v_fma_f32 v44, v44, v170, v170
	v_fma_f32 v45, v45, v170, v170
	v_fma_f32 v46, v46, v170, v170
	v_fma_f32 v47, v47, v170, v170
	v_fma_f32 v40, v40, v170, v170
	v_fma_f32 v41, v41, v170, v170
	v_fma_f32 v42, v42, v170, v170
	v_fma_f32 v43, v43, v170, v170
	v_rcp_f32_e32 v44, v44
	v_rcp_f32_e32 v45, v45
	v_rcp_f32_e32 v46, v46
	v_rcp_f32_e32 v47, v47
	v_rcp_f32_e32 v40, v40
	v_rcp_f32_e32 v41, v41
	v_rcp_f32_e32 v42, v42
	v_rcp_f32_e32 v43, v43
	s_mov_b32 s8, 0xc6000
	v_pk_mul_f32 v[36:37], v[36:37], v[44:45]
	v_pk_mul_f32 v[38:39], v[38:39], v[46:47]
	v_pk_mul_f32 v[32:33], v[32:33], v[40:41]
	v_pk_mul_f32 v[34:35], v[34:35], v[42:43]
	v_cvt_pk_bf16_f32 v44, v36, v37
	v_cvt_pk_bf16_f32 v45, v38, v39
	v_cvt_pk_bf16_f32 v46, v32, v33
	v_cvt_pk_bf16_f32 v47, v34, v35
	v_lshl_add_u64 v[178:179], v[176:177], 0, s[8:9]
	global_store_dwordx4 v[178:179], v[44:47], off
	v_pk_mul_f32 v[20:21], v[28:29], v[20:21]
	v_pk_mul_f32 v[22:23], v[30:31], v[22:23]
	v_pk_mul_f32 v[16:17], v[24:25], v[16:17]
	v_pk_mul_f32 v[18:19], v[26:27], v[18:19]
	s_waitcnt lgkmcnt(1)
	v_mov_b32_e32 v150, v173
	v_pk_mul_f32 v[28:29], v[28:29], v[150:151] op_sel_hi:[1,0]
	v_pk_mul_f32 v[30:31], v[30:31], v[150:151] op_sel_hi:[1,0]
	v_pk_mul_f32 v[24:25], v[24:25], v[150:151] op_sel_hi:[1,0]
	v_pk_mul_f32 v[26:27], v[26:27], v[150:151] op_sel_hi:[1,0]
	v_exp_f32_e32 v28, v28
	v_exp_f32_e32 v29, v29
	v_exp_f32_e32 v30, v30
	v_exp_f32_e32 v31, v31
	v_exp_f32_e32 v24, v24
	v_exp_f32_e32 v25, v25
	v_exp_f32_e32 v26, v26
	v_exp_f32_e32 v27, v27
	v_fma_f32 v28, v28, v172, v172
	v_fma_f32 v29, v29, v172, v172
	v_fma_f32 v30, v30, v172, v172
	v_fma_f32 v31, v31, v172, v172
	v_fma_f32 v24, v24, v172, v172
	v_fma_f32 v25, v25, v172, v172
	v_fma_f32 v26, v26, v172, v172
	v_fma_f32 v27, v27, v172, v172
	v_rcp_f32_e32 v28, v28
	v_rcp_f32_e32 v29, v29
	v_rcp_f32_e32 v30, v30
	v_rcp_f32_e32 v31, v31
	v_rcp_f32_e32 v24, v24
	v_rcp_f32_e32 v25, v25
	v_rcp_f32_e32 v26, v26
	v_rcp_f32_e32 v27, v27
	s_mov_b32 s8, 0xdc000
	v_pk_mul_f32 v[20:21], v[20:21], v[28:29]
	v_pk_mul_f32 v[22:23], v[22:23], v[30:31]
	v_pk_mul_f32 v[16:17], v[16:17], v[24:25]
	v_pk_mul_f32 v[18:19], v[18:19], v[26:27]
	v_cvt_pk_bf16_f32 v28, v20, v21
	v_cvt_pk_bf16_f32 v29, v22, v23
	v_cvt_pk_bf16_f32 v30, v16, v17
	v_cvt_pk_bf16_f32 v31, v18, v19
	v_lshl_add_u64 v[178:179], v[176:177], 0, s[8:9]
	global_store_dwordx4 v[178:179], v[28:31], off
	v_pk_mul_f32 v[4:5], v[12:13], v[4:5]
	v_pk_mul_f32 v[6:7], v[14:15], v[6:7]
	v_pk_mul_f32 v[0:1], v[8:9], v[0:1]
	v_pk_mul_f32 v[2:3], v[10:11], v[2:3]
	s_waitcnt lgkmcnt(0)
	v_mov_b32_e32 v150, v175
	v_pk_mul_f32 v[12:13], v[12:13], v[150:151] op_sel_hi:[1,0]
	v_pk_mul_f32 v[14:15], v[14:15], v[150:151] op_sel_hi:[1,0]
	v_pk_mul_f32 v[8:9], v[8:9], v[150:151] op_sel_hi:[1,0]
	v_pk_mul_f32 v[10:11], v[10:11], v[150:151] op_sel_hi:[1,0]
	v_exp_f32_e32 v12, v12
	v_exp_f32_e32 v13, v13
	v_exp_f32_e32 v14, v14
	v_exp_f32_e32 v15, v15
	v_exp_f32_e32 v8, v8
	v_exp_f32_e32 v9, v9
	v_exp_f32_e32 v10, v10
	v_exp_f32_e32 v11, v11
	v_fma_f32 v12, v12, v174, v174
	v_fma_f32 v13, v13, v174, v174
	v_fma_f32 v14, v14, v174, v174
	v_fma_f32 v15, v15, v174, v174
	v_fma_f32 v8, v8, v174, v174
	v_fma_f32 v9, v9, v174, v174
	v_fma_f32 v10, v10, v174, v174
	v_fma_f32 v11, v11, v174, v174
	v_rcp_f32_e32 v12, v12
	v_rcp_f32_e32 v13, v13
	v_rcp_f32_e32 v14, v14
	v_rcp_f32_e32 v15, v15
	v_rcp_f32_e32 v8, v8
	v_rcp_f32_e32 v9, v9
	v_rcp_f32_e32 v10, v10
	v_rcp_f32_e32 v11, v11
	s_mov_b32 s8, 0xf2000
	v_pk_mul_f32 v[4:5], v[4:5], v[12:13]
	v_pk_mul_f32 v[6:7], v[6:7], v[14:15]
	v_pk_mul_f32 v[0:1], v[0:1], v[8:9]
	v_pk_mul_f32 v[2:3], v[2:3], v[10:11]
	v_cvt_pk_bf16_f32 v12, v4, v5
	v_cvt_pk_bf16_f32 v13, v6, v7
	v_cvt_pk_bf16_f32 v14, v0, v1
	v_cvt_pk_bf16_f32 v15, v2, v3
	v_lshl_add_u64 v[178:179], v[176:177], 0, s[8:9]
	global_store_dwordx4 v[178:179], v[12:15], off
	s_andn2_b64 vcc, exec, s[6:7]
	s_mov_b64 s[6:7], -1
	s_cbranch_vccnz .LBB0_237
	s_andn2_b64 vcc, exec, s[12:13]
	s_cbranch_vccnz .LBB0_236
	s_barrier
	s_branch .LBB0_236

; template <class Epi>
; __device__ __forceinline__ void gemm_phase(LAS unsigned char* lds, const Gemm g, const StaticOrder& S, const Epi& E, int wave_s) {
;     ...
;         const bool has_next = S.next(ui + 1, nxt);
;         const char* nA = has_next ? (const char*)g.A + (size_t)nxt.pm * tstepA : cA; const char* nB = has_next ? (const char*)g.Bt + (size_t)nxt.pn * tstepB : cB;
;     ...
; #pragma unroll
;         for (int a = 0; a < 2; ++a)
; #pragma unroll
;             for (int b = 0; b < 2; ++b)
; #pragma unroll
;                 for (int m = 0; m < 4; ++m)
; #pragma unroll
;                     for (int n = 0; n < 2; ++n) acc[a][b][m][n] = (f32x4){0.f, 0.f, 0.f, 0.f};
.LBB0_1050:
	s_ashr_i32 s25, s24, 31
	s_lshl_b64 s[26:27], s[24:25], 19
	s_add_u32 s26, s0, s26
	s_addc_u32 s27, s1, s27
	s_and_b64 s[28:29], s[6:7], exec
	s_cselect_b32 s9, s27, s31
	s_cselect_b32 s25, s26, s30
	s_ashr_i32 s23, s22, 31
	s_lshl_b64 s[28:29], s[22:23], 19
	s_add_u32 s28, s3, s28
	s_addc_u32 s29, s4, s29
	s_and_b64 s[36:37], s[6:7], exec
	s_cselect_b32 s23, s29, s35
	s_cselect_b32 s52, s28, s34
	s_add_u32 s30, s30, 0x40080
	s_addc_u32 s31, s31, 0
	s_add_u32 s53, s34, 0x100
	v_mov_b32_e32 v0, 0
	s_addc_u32 s54, s35, 0
	s_mov_b32 s55, -2
	v_mov_b32_e32 v1, v0
	v_mov_b32_e32 v2, v0
	v_mov_b32_e32 v3, v0
	v_mov_b32_e32 v4, v0
	v_mov_b32_e32 v5, v0
	v_mov_b32_e32 v6, v0
	v_mov_b32_e32 v7, v0
	v_mov_b32_e32 v8, v0
	v_mov_b32_e32 v9, v0
	v_mov_b32_e32 v10, v0
	v_mov_b32_e32 v11, v0
	v_mov_b32_e32 v12, v0
	v_mov_b32_e32 v13, v0
	v_mov_b32_e32 v14, v0
	v_mov_b32_e32 v15, v0
	s_nop 1
	v_mfma_f32_32x32x16_bf16 v[16:31], v[0:3], v[4:7], 0
	v_mfma_f32_32x32x16_bf16 v[32:47], v[0:3], v[4:7], 0
	v_mfma_f32_32x32x16_bf16 v[48:63], v[0:3], v[4:7], 0
	v_mfma_f32_32x32x16_bf16 v[64:79], v[0:3], v[4:7], 0
	v_mfma_f32_32x32x16_bf16 v[80:95], v[0:3], v[4:7], 0
	v_mfma_f32_32x32x16_bf16 v[96:111], v[0:3], v[4:7], 0
	v_mfma_f32_32x32x16_bf16 v[112:127], v[0:3], v[4:7], 0
	v_readlane_b32 vcc_lo, v254, 7
	v_mbcnt_lo_u32_b32 v226, -1, 0
	v_mbcnt_hi_u32_b32 v226, -1, v226
	v_lshrrev_b32_e32 v227, 1, v226
	v_lshl_add_u32 v227, vcc_lo, 5, v227
	v_and_b32_e32 v228, 1, v226
	v_lshl_add_u32 v229, s8, 8, v227
	v_lshlrev_b32_e32 v229, 6, v229
	v_lshl_add_u32 v229, v228, 5, v229
	global_load_dwordx4 v[230:233], v229, s[16:17]
	global_load_dwordx4 v[234:237], v229, s[16:17] offset:16

; __device__ __forceinline__ unsigned cvtpk(float lo, float hi) { f32x2_t v = {lo, hi}; bf16x2_t b = __builtin_convertvector(v, bf16x2_t); return __builtin_bit_cast(unsigned, b); }
;     __device__ __forceinline__ void operator()(const f32x4 (&acc)[2][2][4][2], const Unit& u, int wr, int wc, int fr, int fq) const {
;         const int row0 = u.pm * BM + wr * 64 + fr, col0 = u.pn * 128 + wc * 32 + 8 * fq;
; #pragma unroll
;         for (int ai = 0; ai < 2; ++ai)
; #pragma unroll
;             for (int m = 0; m < 4; ++m) {
;                 const int row = row0 + ai * HALF + m * 16;
;                 const float rs = 1.0f / sqrtf(ssq_sum(ssq + (size_t)row * 16) * (1.0f / DM) + EPS);
;                 float hv[8];
; #pragma unroll
;                 for (int n = 0; n < 2; ++n)
; #pragma unroll
;                     for (int e = 0; e < 4; ++e) {
;                         const float gg = acc[ai][0][m][n][e] * rs, uu = acc[ai][1][m][n][e] * rs;
;                         const float den = 1.0f + __builtin_amdgcn_exp2f(-gg * LOG2E);
;                         hv[n * 4 + e] = gg * uu * __builtin_amdgcn_rcpf(den);
;                     }
;                 u32x4 w; w.x = cvtpk(hv[0], hv[1]); w.y = cvtpk(hv[2], hv[3]); w.z = cvtpk(hv[4], hv[5]); w.w = cvtpk(hv[6], hv[7]);
;                 *(u32x4*)(H + (size_t)row * DFF + col0) = w;
;             }
.LBB0_1054:
	v_readlane_b32 s9, v254, 7
	v_mbcnt_lo_u32_b32 v144, -1, 0
	v_mbcnt_hi_u32_b32 v144, -1, v144
	v_lshrrev_b32_e32 v145, 1, v144
	v_lshl_add_u32 v145, s9, 5, v145
	v_and_b32_e32 v146, 1, v144
	v_lshl_add_u32 v148, s8, 8, v152
	v_mov_b64_e32 v[146:147], s[14:15]
	v_mad_i64_i32 v[176:177], s[8:9], v148, s51, v[146:147]
	v_lshl_or_b32 v150, s2, 7, v154
	v_mov_b32_e32 v151, 0
	v_lshlrev_b64 v[150:151], 1, v[150:151]
	v_lshl_add_u64 v[176:177], v[176:177], 0, v[150:151]
	v_lshlrev_b32_e32 v145, 3, v145
	v_add_u32_e32 v145, 0x20100, v145
	v_lshlrev_b32_e32 v146, 3, v152
	v_add_u32_e32 v146, 0x20100, v146
	s_mov_b32 s9, 0
	v_pk_add_f32 v[160:161], v[230:231], v[232:233]
	v_pk_add_f32 v[164:165], v[234:235], v[236:237]
	v_pk_add_f32 v[160:161], v[160:161], v[164:165]
	v_add_f32_e32 v160, v160, v161
	s_nop 1
	v_add_f32_dpp v160, v160, v160 quad_perm:[1,0,3,2] row_mask:0xf bank_mask:0xf
	v_fmamk_f32 v160, v160, 0x3a800000, v158
	v_rsq_f32_e32 v161, v160
	s_nop 0
	v_mul_f32_e32 v161, 0xbfb8aa3b, v161
	ds_write_b64 v145, v[160:161]
	s_waitcnt lgkmcnt(0)
	s_barrier
	s_waitcnt vmcnt(0)
	ds_read_b64 v[160:161], v146 offset:0
	ds_read_b64 v[162:163], v146 offset:128
	ds_read_b64 v[164:165], v146 offset:256
	ds_read_b64 v[166:167], v146 offset:384
	ds_read_b64 v[168:169], v146 offset:1024
	ds_read_b64 v[170:171], v146 offset:1152
	ds_read_b64 v[172:173], v146 offset:1280
	ds_read_b64 v[174:175], v146 offset:1408
	v_pk_mul_f32 v[116:117], v[124:125], v[116:117]
	v_pk_mul_f32 v[118:119], v[126:127], v[118:119]
	v_pk_mul_f32 v[112:113], v[120:121], v[112:113]
	v_pk_mul_f32 v[114:115], v[122:123], v[114:115]
	s_waitcnt lgkmcnt(7)
	v_mov_b32_e32 v150, v161
	v_pk_mul_f32 v[124:125], v[124:125], v[150:151] op_sel_hi:[1,0]
	v_pk_mul_f32 v[126:127], v[126:127], v[150:151] op_sel_hi:[1,0]
	v_pk_mul_f32 v[120:121], v[120:121], v[150:151] op_sel_hi:[1,0]
	v_pk_mul_f32 v[122:123], v[122:123], v[150:151] op_sel_hi:[1,0]
	v_exp_f32_e32 v124, v124
	v_exp_f32_e32 v125, v125
	v_exp_f32_e32 v126, v126
	v_exp_f32_e32 v127, v127
	v_exp_f32_e32 v120, v120
	v_exp_f32_e32 v121, v121
	v_exp_f32_e32 v122, v122
	v_exp_f32_e32 v123, v123
	v_fma_f32 v124, v124, v160, v160
	v_fma_f32 v125, v125, v160, v160
	v_fma_f32 v126, v126, v160, v160
	v_fma_f32 v127, v127, v160, v160
	v_fma_f32 v120, v120, v160, v160
	v_fma_f32 v121, v121, v160, v160
	v_fma_f32 v122, v122, v160, v160
	v_fma_f32 v123, v123, v160, v160
	v_rcp_f32_e32 v124, v124
	v_rcp_f32_e32 v125, v125
	v_rcp_f32_e32 v126, v126
	v_rcp_f32_e32 v127, v127
	v_rcp_f32_e32 v120, v120
	v_rcp_f32_e32 v121, v121
	v_rcp_f32_e32 v122, v122
	v_rcp_f32_e32 v123, v123
	v_pk_mul_f32 v[116:117], v[116:117], v[124:125]
	v_pk_mul_f32 v[118:119], v[118:119], v[126:127]
	v_pk_mul_f32 v[112:113], v[112:113], v[120:121]
	v_pk_mul_f32 v[114:115], v[114:115], v[122:123]
	v_cvt_pk_bf16_f32 v124, v116, v117
	v_cvt_pk_bf16_f32 v125, v118, v119
	v_cvt_pk_bf16_f32 v126, v112, v113
	v_cvt_pk_bf16_f32 v127, v114, v115
	global_store_dwordx4 v[176:177], v[124:127], off
	v_pk_mul_f32 v[100:101], v[108:109], v[100:101]
	v_pk_mul_f32 v[102:103], v[110:111], v[102:103]
	v_pk_mul_f32 v[96:97], v[104:105], v[96:97]
	v_pk_mul_f32 v[98:99], v[106:107], v[98:99]
	s_waitcnt lgkmcnt(6)
	v_mov_b32_e32 v150, v163
	v_pk_mul_f32 v[108:109], v[108:109], v[150:151] op_sel_hi:[1,0]
	v_pk_mul_f32 v[110:111], v[110:111], v[150:151] op_sel_hi:[1,0]
	v_pk_mul_f32 v[104:105], v[104:105], v[150:151] op_sel_hi:[1,0]
	v_pk_mul_f32 v[106:107], v[106:107], v[150:151] op_sel_hi:[1,0]
	v_exp_f32_e32 v108, v108
	v_exp_f32_e32 v109, v109
	v_exp_f32_e32 v110, v110
	v_exp_f32_e32 v111, v111
	v_exp_f32_e32 v104, v104
	v_exp_f32_e32 v105, v105
	v_exp_f32_e32 v106, v106
	v_exp_f32_e32 v107, v107
	v_fma_f32 v108, v108, v162, v162
	v_fma_f32 v109, v109, v162, v162
	v_fma_f32 v110, v110, v162, v162
	v_fma_f32 v111, v111, v162, v162
	v_fma_f32 v104, v104, v162, v162
	v_fma_f32 v105, v105, v162, v162
	v_fma_f32 v106, v106, v162, v162
	v_fma_f32 v107, v107, v162, v162
	v_rcp_f32_e32 v108, v108
	v_rcp_f32_e32 v109, v109
	v_rcp_f32_e32 v110, v110
	v_rcp_f32_e32 v111, v111
	v_rcp_f32_e32 v104, v104
	v_rcp_f32_e32 v105, v105
	v_rcp_f32_e32 v106, v106
	v_rcp_f32_e32 v107, v107
	s_mov_b32 s8, 0x16000
	v_pk_mul_f32 v[100:101], v[100:101], v[108:109]
	v_pk_mul_f32 v[102:103], v[102:103], v[110:111]
	v_pk_mul_f32 v[96:97], v[96:97], v[104:105]
	v_pk_mul_f32 v[98:99], v[98:99], v[106:107]
	v_cvt_pk_bf16_f32 v108, v100, v101
	v_cvt_pk_bf16_f32 v109, v102, v103
	v_cvt_pk_bf16_f32 v110, v96, v97
	v_cvt_pk_bf16_f32 v111, v98, v99
	v_lshl_add_u64 v[178:179], v[176:177], 0, s[8:9]
	global_store_dwordx4 v[178:179], v[108:111], off
	v_pk_mul_f32 v[84:85], v[92:93], v[84:85]
	v_pk_mul_f32 v[86:87], v[94:95], v[86:87]
	v_pk_mul_f32 v[80:81], v[88:89], v[80:81]
	v_pk_mul_f32 v[82:83], v[90:91], v[82:83]
	s_waitcnt lgkmcnt(5)
	v_mov_b32_e32 v150, v165
	v_pk_mul_f32 v[92:93], v[92:93], v[150:151] op_sel_hi:[1,0]
	v_pk_mul_f32 v[94:95], v[94:95], v[150:151] op_sel_hi:[1,0]
	v_pk_mul_f32 v[88:89], v[88:89], v[150:151] op_sel_hi:[1,0]
	v_pk_mul_f32 v[90:91], v[90:91], v[150:151] op_sel_hi:[1,0]
	v_exp_f32_e32 v92, v92
	v_exp_f32_e32 v93, v93
	v_exp_f32_e32 v94, v94
	v_exp_f32_e32 v95, v95
	v_exp_f32_e32 v88, v88
	v_exp_f32_e32 v89, v89
	v_exp_f32_e32 v90, v90
	v_exp_f32_e32 v91, v91
	v_fma_f32 v92, v92, v164, v164
	v_fma_f32 v93, v93, v164, v164
	v_fma_f32 v94, v94, v164, v164
	v_fma_f32 v95, v95, v164, v164
	v_fma_f32 v88, v88, v164, v164
	v_fma_f32 v89, v89, v164, v164
	v_fma_f32 v90, v90, v164, v164
	v_fma_f32 v91, v91, v164, v164
	v_rcp_f32_e32 v92, v92
	v_rcp_f32_e32 v93, v93
	v_rcp_f32_e32 v94, v94
	v_rcp_f32_e32 v95, v95
	v_rcp_f32_e32 v88, v88
	v_rcp_f32_e32 v89, v89
	v_rcp_f32_e32 v90, v90
	v_rcp_f32_e32 v91, v91
	s_mov_b32 s8, 0x2c000
	v_pk_mul_f32 v[84:85], v[84:85], v[92:93]
	v_pk_mul_f32 v[86:87], v[86:87], v[94:95]
	v_pk_mul_f32 v[80:81], v[80:81], v[88:89]
	v_pk_mul_f32 v[82:83], v[82:83], v[90:91]
	v_cvt_pk_bf16_f32 v92, v84, v85
	v_cvt_pk_bf16_f32 v93, v86, v87
	v_cvt_pk_bf16_f32 v94, v80, v81
	v_cvt_pk_bf16_f32 v95, v82, v83
	v_lshl_add_u64 v[178:179], v[176:177], 0, s[8:9]
	global_store_dwordx4 v[178:179], v[92:95], off
	v_pk_mul_f32 v[68:69], v[76:77], v[68:69]
	v_pk_mul_f32 v[70:71], v[78:79], v[70:71]
	v_pk_mul_f32 v[64:65], v[72:73], v[64:65]
	v_pk_mul_f32 v[66:67], v[74:75], v[66:67]
	s_waitcnt lgkmcnt(4)
; __device__ __forceinline__ unsigned cvtpk(float lo, float hi) { f32x2_t v = {lo, hi}; bf16x2_t b = __builtin_convertvector(v, bf16x2_t); return __builtin_bit_cast(unsigned, b); }
;     __device__ __forceinline__ void operator()(const f32x4 (&acc)[2][2][4][2], const Unit& u, int wr, int wc, int fr, int fq) const {
;     ...
;                     for (int e = 0; e < 4; ++e) {
;                         const float gg = acc[ai][0][m][n][e] * rs, uu = acc[ai][1][m][n][e] * rs;
;                         const float den = 1.0f + __builtin_amdgcn_exp2f(-gg * LOG2E);
;                         hv[n * 4 + e] = gg * uu * __builtin_amdgcn_rcpf(den);
;                     }
;                 u32x4 w; w.x = cvtpk(hv[0], hv[1]); w.y = cvtpk(hv[2], hv[3]); w.z = cvtpk(hv[4], hv[5]); w.w = cvtpk(hv[6], hv[7]);
;                 *(u32x4*)(H + (size_t)row * DFF + col0) = w;
	v_mov_b32_e32 v150, v167
	v_pk_mul_f32 v[76:77], v[76:77], v[150:151] op_sel_hi:[1,0]
	v_pk_mul_f32 v[78:79], v[78:79], v[150:151] op_sel_hi:[1,0]
	v_pk_mul_f32 v[72:73], v[72:73], v[150:151] op_sel_hi:[1,0]
	v_pk_mul_f32 v[74:75], v[74:75], v[150:151] op_sel_hi:[1,0]
	v_exp_f32_e32 v76, v76
	v_exp_f32_e32 v77, v77
	v_exp_f32_e32 v78, v78
	v_exp_f32_e32 v79, v79
	v_exp_f32_e32 v72, v72
	v_exp_f32_e32 v73, v73
	v_exp_f32_e32 v74, v74
	v_exp_f32_e32 v75, v75
	v_fma_f32 v76, v76, v166, v166
	v_fma_f32 v77, v77, v166, v166
	v_fma_f32 v78, v78, v166, v166
	v_fma_f32 v79, v79, v166, v166
	v_fma_f32 v72, v72, v166, v166
	v_fma_f32 v73, v73, v166, v166
	v_fma_f32 v74, v74, v166, v166
	v_fma_f32 v75, v75, v166, v166
	v_rcp_f32_e32 v76, v76
	v_rcp_f32_e32 v77, v77
	v_rcp_f32_e32 v78, v78
	v_rcp_f32_e32 v79, v79
	v_rcp_f32_e32 v72, v72
	v_rcp_f32_e32 v73, v73
	v_rcp_f32_e32 v74, v74
	v_rcp_f32_e32 v75, v75
	s_mov_b32 s8, 0x42000
	v_pk_mul_f32 v[68:69], v[68:69], v[76:77]
	v_pk_mul_f32 v[70:71], v[70:71], v[78:79]
	v_pk_mul_f32 v[64:65], v[64:65], v[72:73]
	v_pk_mul_f32 v[66:67], v[66:67], v[74:75]
	v_cvt_pk_bf16_f32 v76, v68, v69
	v_cvt_pk_bf16_f32 v77, v70, v71
	v_cvt_pk_bf16_f32 v78, v64, v65
	v_cvt_pk_bf16_f32 v79, v66, v67
	v_lshl_add_u64 v[178:179], v[176:177], 0, s[8:9]
	global_store_dwordx4 v[178:179], v[76:79], off
	v_pk_mul_f32 v[52:53], v[60:61], v[52:53]
	v_pk_mul_f32 v[54:55], v[62:63], v[54:55]
	v_pk_mul_f32 v[48:49], v[56:57], v[48:49]
	v_pk_mul_f32 v[50:51], v[58:59], v[50:51]
	s_waitcnt lgkmcnt(3)
	v_mov_b32_e32 v150, v169
	v_pk_mul_f32 v[60:61], v[60:61], v[150:151] op_sel_hi:[1,0]
	v_pk_mul_f32 v[62:63], v[62:63], v[150:151] op_sel_hi:[1,0]
	v_pk_mul_f32 v[56:57], v[56:57], v[150:151] op_sel_hi:[1,0]
	v_pk_mul_f32 v[58:59], v[58:59], v[150:151] op_sel_hi:[1,0]
	v_exp_f32_e32 v60, v60
	v_exp_f32_e32 v61, v61
	v_exp_f32_e32 v62, v62
	v_exp_f32_e32 v63, v63
	v_exp_f32_e32 v56, v56
	v_exp_f32_e32 v57, v57
	v_exp_f32_e32 v58, v58
	v_exp_f32_e32 v59, v59
	v_fma_f32 v60, v60, v168, v168
	v_fma_f32 v61, v61, v168, v168
	v_fma_f32 v62, v62, v168, v168
	v_fma_f32 v63, v63, v168, v168
	v_fma_f32 v56, v56, v168, v168
	v_fma_f32 v57, v57, v168, v168
	v_fma_f32 v58, v58, v168, v168
	v_fma_f32 v59, v59, v168, v168
	v_rcp_f32_e32 v60, v60
	v_rcp_f32_e32 v61, v61
	v_rcp_f32_e32 v62, v62
	v_rcp_f32_e32 v63, v63
	v_rcp_f32_e32 v56, v56
	v_rcp_f32_e32 v57, v57
	v_rcp_f32_e32 v58, v58
	v_rcp_f32_e32 v59, v59
	s_mov_b32 s8, 0xb0000
	v_pk_mul_f32 v[52:53], v[52:53], v[60:61]
	v_pk_mul_f32 v[54:55], v[54:55], v[62:63]
	v_pk_mul_f32 v[48:49], v[48:49], v[56:57]
	v_pk_mul_f32 v[50:51], v[50:51], v[58:59]
	v_cvt_pk_bf16_f32 v60, v52, v53
	v_cvt_pk_bf16_f32 v61, v54, v55
	v_cvt_pk_bf16_f32 v62, v48, v49
	v_cvt_pk_bf16_f32 v63, v50, v51
	v_lshl_add_u64 v[178:179], v[176:177], 0, s[8:9]
	global_store_dwordx4 v[178:179], v[60:63], off
	v_pk_mul_f32 v[36:37], v[44:45], v[36:37]
	v_pk_mul_f32 v[38:39], v[46:47], v[38:39]
	v_pk_mul_f32 v[32:33], v[40:41], v[32:33]
	v_pk_mul_f32 v[34:35], v[42:43], v[34:35]
	s_waitcnt lgkmcnt(2)
; __device__ __forceinline__ unsigned cvtpk(float lo, float hi) { f32x2_t v = {lo, hi}; bf16x2_t b = __builtin_convertvector(v, bf16x2_t); return __builtin_bit_cast(unsigned, b); }
; #define PG8_BAR __builtin_amdgcn_s_barrier()
; template <class Epi>
; __device__ __forceinline__ void gemm_phase(LAS unsigned char* lds, const Gemm g, const StaticOrder& S, const Epi& E, int wave_s) {
;     ...
;         if (!has_next) break;
; #pragma unroll
;         for (int a = 0; a < 2; ++a)
; #pragma unroll
;             for (int b = 0; b < 2; ++b)
; #pragma unroll
;                 for (int m = 0; m < 4; ++m)
; #pragma unroll
;                     for (int n = 0; n < 2; ++n) acc[a][b][m][n] = (f32x4){0.f, 0.f, 0.f, 0.f};
;         cur = nxt; cA = nA; cB = nB; ++ui;
;         if (wr == 1) PG8_BAR;
;     __device__ __forceinline__ void operator()(const f32x4 (&acc)[2][2][4][2], const Unit& u, int wr, int wc, int fr, int fq) const {
;     ...
;                     for (int e = 0; e < 4; ++e) {
;                         const float gg = acc[ai][0][m][n][e] * rs, uu = acc[ai][1][m][n][e] * rs;
;                         const float den = 1.0f + __builtin_amdgcn_exp2f(-gg * LOG2E);
;                         hv[n * 4 + e] = gg * uu * __builtin_amdgcn_rcpf(den);
;                     }
;                 u32x4 w; w.x = cvtpk(hv[0], hv[1]); w.y = cvtpk(hv[2], hv[3]); w.z = cvtpk(hv[4], hv[5]); w.w = cvtpk(hv[6], hv[7]);
;                 *(u32x4*)(H + (size_t)row * DFF + col0) = w;
	v_mov_b32_e32 v150, v171
	v_pk_mul_f32 v[44:45], v[44:45], v[150:151] op_sel_hi:[1,0]
	v_pk_mul_f32 v[46:47], v[46:47], v[150:151] op_sel_hi:[1,0]
	v_pk_mul_f32 v[40:41], v[40:41], v[150:151] op_sel_hi:[1,0]
	v_pk_mul_f32 v[42:43], v[42:43], v[150:151] op_sel_hi:[1,0]
	v_exp_f32_e32 v44, v44
	v_exp_f32_e32 v45, v45
	v_exp_f32_e32 v46, v46
	v_exp_f32_e32 v47, v47
	v_exp_f32_e32 v40, v40
	v_exp_f32_e32 v41, v41
	v_exp_f32_e32 v42, v42
	v_exp_f32_e32 v43, v43
	v_fma_f32 v44, v44, v170, v170
	v_fma_f32 v45, v45, v170, v170
	v_fma_f32 v46, v46, v170, v170
	v_fma_f32 v47, v47, v170, v170
	v_fma_f32 v40, v40, v170, v170
	v_fma_f32 v41, v41, v170, v170
	v_fma_f32 v42, v42, v170, v170
	v_fma_f32 v43, v43, v170, v170
	v_rcp_f32_e32 v44, v44
	v_rcp_f32_e32 v45, v45
	v_rcp_f32_e32 v46, v46
	v_rcp_f32_e32 v47, v47
	v_rcp_f32_e32 v40, v40
	v_rcp_f32_e32 v41, v41
	v_rcp_f32_e32 v42, v42
	v_rcp_f32_e32 v43, v43
	s_mov_b32 s8, 0xc6000
	v_pk_mul_f32 v[36:37], v[36:37], v[44:45]
	v_pk_mul_f32 v[38:39], v[38:39], v[46:47]
	v_pk_mul_f32 v[32:33], v[32:33], v[40:41]
	v_pk_mul_f32 v[34:35], v[34:35], v[42:43]
	v_cvt_pk_bf16_f32 v44, v36, v37
	v_cvt_pk_bf16_f32 v45, v38, v39
	v_cvt_pk_bf16_f32 v46, v32, v33
	v_cvt_pk_bf16_f32 v47, v34, v35
	v_lshl_add_u64 v[178:179], v[176:177], 0, s[8:9]
	global_store_dwordx4 v[178:179], v[44:47], off
	v_pk_mul_f32 v[20:21], v[28:29], v[20:21]
	v_pk_mul_f32 v[22:23], v[30:31], v[22:23]
	v_pk_mul_f32 v[16:17], v[24:25], v[16:17]
	v_pk_mul_f32 v[18:19], v[26:27], v[18:19]
	s_waitcnt lgkmcnt(1)
	v_mov_b32_e32 v150, v173
	v_pk_mul_f32 v[28:29], v[28:29], v[150:151] op_sel_hi:[1,0]
	v_pk_mul_f32 v[30:31], v[30:31], v[150:151] op_sel_hi:[1,0]
	v_pk_mul_f32 v[24:25], v[24:25], v[150:151] op_sel_hi:[1,0]
	v_pk_mul_f32 v[26:27], v[26:27], v[150:151] op_sel_hi:[1,0]
	v_exp_f32_e32 v28, v28
	v_exp_f32_e32 v29, v29
	v_exp_f32_e32 v30, v30
	v_exp_f32_e32 v31, v31
	v_exp_f32_e32 v24, v24
	v_exp_f32_e32 v25, v25
	v_exp_f32_e32 v26, v26
	v_exp_f32_e32 v27, v27
	v_fma_f32 v28, v28, v172, v172
	v_fma_f32 v29, v29, v172, v172
	v_fma_f32 v30, v30, v172, v172
	v_fma_f32 v31, v31, v172, v172
	v_fma_f32 v24, v24, v172, v172
	v_fma_f32 v25, v25, v172, v172
	v_fma_f32 v26, v26, v172, v172
	v_fma_f32 v27, v27, v172, v172
	v_rcp_f32_e32 v28, v28
	v_rcp_f32_e32 v29, v29
	v_rcp_f32_e32 v30, v30
	v_rcp_f32_e32 v31, v31
	v_rcp_f32_e32 v24, v24
	v_rcp_f32_e32 v25, v25
	v_rcp_f32_e32 v26, v26
	v_rcp_f32_e32 v27, v27
	s_mov_b32 s8, 0xdc000
	v_pk_mul_f32 v[20:21], v[20:21], v[28:29]
	v_pk_mul_f32 v[22:23], v[22:23], v[30:31]
	v_pk_mul_f32 v[16:17], v[16:17], v[24:25]
	v_pk_mul_f32 v[18:19], v[18:19], v[26:27]
	v_cvt_pk_bf16_f32 v28, v20, v21
	v_cvt_pk_bf16_f32 v29, v22, v23
	v_cvt_pk_bf16_f32 v30, v16, v17
	v_cvt_pk_bf16_f32 v31, v18, v19
	v_lshl_add_u64 v[178:179], v[176:177], 0, s[8:9]
	global_store_dwordx4 v[178:179], v[28:31], off
	v_pk_mul_f32 v[4:5], v[12:13], v[4:5]
	v_pk_mul_f32 v[6:7], v[14:15], v[6:7]
	v_pk_mul_f32 v[0:1], v[8:9], v[0:1]
	v_pk_mul_f32 v[2:3], v[10:11], v[2:3]
	s_waitcnt lgkmcnt(0)
	v_mov_b32_e32 v150, v175
	v_pk_mul_f32 v[12:13], v[12:13], v[150:151] op_sel_hi:[1,0]
	v_pk_mul_f32 v[14:15], v[14:15], v[150:151] op_sel_hi:[1,0]
	v_pk_mul_f32 v[8:9], v[8:9], v[150:151] op_sel_hi:[1,0]
	v_pk_mul_f32 v[10:11], v[10:11], v[150:151] op_sel_hi:[1,0]
	v_exp_f32_e32 v12, v12
	v_exp_f32_e32 v13, v13
	v_exp_f32_e32 v14, v14
	v_exp_f32_e32 v15, v15
	v_exp_f32_e32 v8, v8
	v_exp_f32_e32 v9, v9
	v_exp_f32_e32 v10, v10
	v_exp_f32_e32 v11, v11
	v_fma_f32 v12, v12, v174, v174
	v_fma_f32 v13, v13, v174, v174
	v_fma_f32 v14, v14, v174, v174
	v_fma_f32 v15, v15, v174, v174
	v_fma_f32 v8, v8, v174, v174
	v_fma_f32 v9, v9, v174, v174
	v_fma_f32 v10, v10, v174, v174
	v_fma_f32 v11, v11, v174, v174
	v_rcp_f32_e32 v12, v12
	v_rcp_f32_e32 v13, v13
	v_rcp_f32_e32 v14, v14
	v_rcp_f32_e32 v15, v15
	v_rcp_f32_e32 v8, v8
	v_rcp_f32_e32 v9, v9
	v_rcp_f32_e32 v10, v10
	v_rcp_f32_e32 v11, v11
	s_mov_b32 s8, 0xf2000
	v_pk_mul_f32 v[4:5], v[4:5], v[12:13]
	v_pk_mul_f32 v[6:7], v[6:7], v[14:15]
	v_pk_mul_f32 v[0:1], v[0:1], v[8:9]
	v_pk_mul_f32 v[2:3], v[2:3], v[10:11]
	v_cvt_pk_bf16_f32 v12, v4, v5
	v_cvt_pk_bf16_f32 v13, v6, v7
	v_cvt_pk_bf16_f32 v14, v0, v1
	v_cvt_pk_bf16_f32 v15, v2, v3
	v_lshl_add_u64 v[178:179], v[176:177], 0, s[8:9]
	global_store_dwordx4 v[178:179], v[12:15], off
	s_andn2_b64 vcc, exec, s[6:7]
	s_mov_b64 s[6:7], -1
	s_cbranch_vccnz .LBB0_1047
	s_andn2_b64 vcc, exec, s[12:13]
	s_cbranch_vccnz .LBB0_1046
	s_barrier
	s_branch .LBB0_1046
